# P0 layer-B weight transposes: the 32 per-lane gain loads of an item issued together behind the weight loads (v150-181) instead of 16 serial pairs; on top of v92
# baseline (speedup 1.0000x reference)
; template <bool F16 = false>
; __device__ __forceinline__ void p0_transpose_item(const float* W, int K, int N, bf16* WT, const float* gk, LAS float* scr, int item, int lane) {
;     ...
;     for (int i = 0; i < 32; ++i) { const int kk = 2 * i + (lane >> 5); wv[i] = __builtin_nontemporal_load(W + (size_t)(k0 + kk) * N + n0 + (lane & 31)); }
; #pragma unroll
;     for (int i = 0; i < 32; ++i) { const int kk = 2 * i + (lane >> 5); const float gsc = gk ? gk[k0 + kk] : 1.0f; scr[kk * 33 + (lane & 31)] = wv[i] * gsc; }
.LBB0_20:
	s_andn2_b64 vcc, exec, s[8:9]
	s_cbranch_vccnz .LBB0_22
	s_add_i32 s0, s23, 0xffffea00
	s_lshr_b32 s0, s0, 1
	s_and_b32 s8, s0, 0x3c0
	s_add_i32 s0, s16, 0xfffd4000
	s_and_b32 s2, s0, 0xfe0
	v_or_b32_e32 v71, s8, v2
	s_lshl_b32 s0, s2, 2
	v_lshl_add_u64 v[22:23], v[16:17], 0, s[0:1]
	v_lshlrev_b32_e32 v4, 14, v71
	v_lshl_add_u64 v[22:23], v[22:23], 0, v[4:5]
	v_add_co_u32_e32 v74, vcc, 0x8000, v22
	global_load_dword v4, v[22:23], off nt
	s_nop 0
	v_addc_co_u32_e32 v75, vcc, 0, v23, vcc
	global_load_dword v73, v[74:75], off nt
	v_add_co_u32_e32 v74, vcc, 0x10000, v22
	s_lshl_b32 s0, s8, 1
	s_nop 0
	v_addc_co_u32_e32 v75, vcc, 0, v23, vcc
	global_load_dword v76, v[74:75], off nt
	v_add_co_u32_e32 v74, vcc, 0x18000, v22
	s_nop 1
	v_addc_co_u32_e32 v75, vcc, 0, v23, vcc
	global_load_dword v77, v[74:75], off nt
	v_add_co_u32_e32 v74, vcc, 0x20000, v22
	s_nop 1
	v_addc_co_u32_e32 v75, vcc, 0, v23, vcc
	global_load_dword v78, v[74:75], off nt
	v_add_co_u32_e32 v74, vcc, 0x28000, v22
	s_nop 1
	v_addc_co_u32_e32 v75, vcc, 0, v23, vcc
	global_load_dword v79, v[74:75], off nt
	v_add_co_u32_e32 v74, vcc, 0x30000, v22
	s_nop 1
	v_addc_co_u32_e32 v75, vcc, 0, v23, vcc
	global_load_dword v80, v[74:75], off nt
	v_add_co_u32_e32 v74, vcc, 0x38000, v22
	s_nop 1
	v_addc_co_u32_e32 v75, vcc, 0, v23, vcc
	global_load_dword v81, v[74:75], off nt
	v_add_co_u32_e32 v74, vcc, 0x40000, v22
	s_nop 1
	v_addc_co_u32_e32 v75, vcc, 0, v23, vcc
	global_load_dword v82, v[74:75], off nt
	v_add_co_u32_e32 v74, vcc, 0x48000, v22
	s_nop 1
	v_addc_co_u32_e32 v75, vcc, 0, v23, vcc
	global_load_dword v83, v[74:75], off nt
	v_add_co_u32_e32 v74, vcc, 0x50000, v22
	s_nop 1
	v_addc_co_u32_e32 v75, vcc, 0, v23, vcc
	global_load_dword v84, v[74:75], off nt
	v_add_co_u32_e32 v74, vcc, 0x58000, v22
	s_nop 1
	v_addc_co_u32_e32 v75, vcc, 0, v23, vcc
	global_load_dword v85, v[74:75], off nt
	v_add_co_u32_e32 v74, vcc, 0x60000, v22
	s_nop 1
	v_addc_co_u32_e32 v75, vcc, 0, v23, vcc
	global_load_dword v86, v[74:75], off nt
	v_add_co_u32_e32 v74, vcc, 0x68000, v22
	s_nop 1
	v_addc_co_u32_e32 v75, vcc, 0, v23, vcc
	global_load_dword v87, v[74:75], off nt
	v_add_co_u32_e32 v74, vcc, 0x70000, v22
	s_nop 1
	v_addc_co_u32_e32 v75, vcc, 0, v23, vcc
	global_load_dword v88, v[74:75], off nt
	v_add_co_u32_e32 v74, vcc, 0x78000, v22
	s_nop 1
	v_addc_co_u32_e32 v75, vcc, 0, v23, vcc
	global_load_dword v89, v[74:75], off nt
	v_add_co_u32_e32 v74, vcc, 0x80000, v22
	s_nop 1
	v_addc_co_u32_e32 v75, vcc, 0, v23, vcc
	global_load_dword v90, v[74:75], off nt
	v_add_co_u32_e32 v74, vcc, 0x88000, v22
	s_nop 1
	v_addc_co_u32_e32 v75, vcc, 0, v23, vcc
	global_load_dword v91, v[74:75], off nt
	v_add_co_u32_e32 v74, vcc, 0x90000, v22
	s_nop 1
	v_addc_co_u32_e32 v75, vcc, 0, v23, vcc
	global_load_dword v92, v[74:75], off nt
	v_add_co_u32_e32 v74, vcc, 0x98000, v22
	s_nop 1
	v_addc_co_u32_e32 v75, vcc, 0, v23, vcc
	global_load_dword v93, v[74:75], off nt
	v_add_co_u32_e32 v74, vcc, 0xa0000, v22
	s_nop 1
	v_addc_co_u32_e32 v75, vcc, 0, v23, vcc
	global_load_dword v94, v[74:75], off nt
	v_add_co_u32_e32 v74, vcc, 0xa8000, v22
	s_nop 1
	v_addc_co_u32_e32 v75, vcc, 0, v23, vcc
	global_load_dword v95, v[74:75], off nt
	v_add_co_u32_e32 v74, vcc, 0xb0000, v22
	s_nop 1
	v_addc_co_u32_e32 v75, vcc, 0, v23, vcc
	global_load_dword v96, v[74:75], off nt
	v_add_co_u32_e32 v74, vcc, 0xb8000, v22
	s_nop 1
	v_addc_co_u32_e32 v75, vcc, 0, v23, vcc
	global_load_dword v97, v[74:75], off nt
	v_add_co_u32_e32 v74, vcc, 0xc0000, v22
	s_nop 1
	v_addc_co_u32_e32 v75, vcc, 0, v23, vcc
	global_load_dword v98, v[74:75], off nt
	v_add_co_u32_e32 v74, vcc, 0xc8000, v22
	s_nop 1
	v_addc_co_u32_e32 v75, vcc, 0, v23, vcc
	global_load_dword v99, v[74:75], off nt
	v_add_co_u32_e32 v74, vcc, 0xd0000, v22
	s_nop 1
	v_addc_co_u32_e32 v75, vcc, 0, v23, vcc
	global_load_dword v100, v[74:75], off nt
	v_add_co_u32_e32 v74, vcc, 0xd8000, v22
	s_nop 1
	v_addc_co_u32_e32 v75, vcc, 0, v23, vcc
	global_load_dword v101, v[74:75], off nt
	v_add_co_u32_e32 v74, vcc, 0xe0000, v22
	s_nop 1
	v_addc_co_u32_e32 v75, vcc, 0, v23, vcc
	global_load_dword v102, v[74:75], off nt
	v_add_co_u32_e32 v74, vcc, 0xe8000, v22
	s_nop 1
	v_addc_co_u32_e32 v75, vcc, 0, v23, vcc
	global_load_dword v103, v[74:75], off nt
	v_add_co_u32_e32 v74, vcc, 0xf0000, v22
	s_nop 1
	v_addc_co_u32_e32 v75, vcc, 0, v23, vcc
	v_add_co_u32_e32 v22, vcc, 0xf8000, v22
	global_load_dword v74, v[74:75], off nt
	s_nop 0
	v_addc_co_u32_e32 v23, vcc, 0, v23, vcc
	global_load_dword v22, v[22:23], off nt
	v_or_b32_e32 v150, s8, v2
	v_lshlrev_b32_e32 v150, 2, v150
	global_load_dword v150, v150, s[4:5]
	v_or_b32_e32 v151, s8, v32
	v_lshlrev_b32_e32 v151, 2, v151
	global_load_dword v151, v151, s[4:5]
	v_or_b32_e32 v152, s8, v30
	v_lshlrev_b32_e32 v152, 2, v152
	global_load_dword v152, v152, s[4:5]
	v_or_b32_e32 v153, s8, v33
	v_lshlrev_b32_e32 v153, 2, v153
	global_load_dword v153, v153, s[4:5]
	v_or_b32_e32 v154, s8, v34
	v_lshlrev_b32_e32 v154, 2, v154
	global_load_dword v154, v154, s[4:5]
	v_or_b32_e32 v155, s8, v35
	v_lshlrev_b32_e32 v155, 2, v155
	global_load_dword v155, v155, s[4:5]
	v_or_b32_e32 v156, s8, v36
	v_lshlrev_b32_e32 v156, 2, v156
	global_load_dword v156, v156, s[4:5]
	v_or_b32_e32 v157, s8, v37
	v_lshlrev_b32_e32 v157, 2, v157
	global_load_dword v157, v157, s[4:5]
	v_or_b32_e32 v158, s8, v38
	v_lshlrev_b32_e32 v158, 2, v158
	global_load_dword v158, v158, s[4:5]
	v_or_b32_e32 v159, s8, v39
	v_lshlrev_b32_e32 v159, 2, v159
	global_load_dword v159, v159, s[4:5]
	v_or_b32_e32 v160, s8, v40
	v_lshlrev_b32_e32 v160, 2, v160
	global_load_dword v160, v160, s[4:5]
	v_or_b32_e32 v161, s8, v41
; template <bool F16 = false>
; __device__ __forceinline__ void p0_transpose_item(const float* W, int K, int N, bf16* WT, const float* gk, LAS float* scr, int item, int lane) {
;     ...
;     for (int i = 0; i < 32; ++i) { const int kk = 2 * i + (lane >> 5); const float gsc = gk ? gk[k0 + kk] : 1.0f; scr[kk * 33 + (lane & 31)] = wv[i] * gsc; }
	v_lshlrev_b32_e32 v161, 2, v161
	global_load_dword v161, v161, s[4:5]
	v_or_b32_e32 v162, s8, v42
	v_lshlrev_b32_e32 v162, 2, v162
	global_load_dword v162, v162, s[4:5]
	v_or_b32_e32 v163, s8, v43
	v_lshlrev_b32_e32 v163, 2, v163
	global_load_dword v163, v163, s[4:5]
	v_or_b32_e32 v164, s8, v45
	v_lshlrev_b32_e32 v164, 2, v164
	global_load_dword v164, v164, s[4:5]
	v_or_b32_e32 v165, s8, v46
	v_lshlrev_b32_e32 v165, 2, v165
	global_load_dword v165, v165, s[4:5]
	v_or_b32_e32 v166, s8, v47
	v_lshlrev_b32_e32 v166, 2, v166
	global_load_dword v166, v166, s[4:5]
	v_or_b32_e32 v167, s8, v48
	v_lshlrev_b32_e32 v167, 2, v167
	global_load_dword v167, v167, s[4:5]
	v_or_b32_e32 v168, s8, v49
	v_lshlrev_b32_e32 v168, 2, v168
	global_load_dword v168, v168, s[4:5]
	v_or_b32_e32 v169, s8, v50
	v_lshlrev_b32_e32 v169, 2, v169
	global_load_dword v169, v169, s[4:5]
	v_or_b32_e32 v170, s8, v51
	v_lshlrev_b32_e32 v170, 2, v170
	global_load_dword v170, v170, s[4:5]
	v_or_b32_e32 v171, s8, v52
	v_lshlrev_b32_e32 v171, 2, v171
	global_load_dword v171, v171, s[4:5]
	v_or_b32_e32 v172, s8, v53
	v_lshlrev_b32_e32 v172, 2, v172
	global_load_dword v172, v172, s[4:5]
	v_or_b32_e32 v173, s8, v54
	v_lshlrev_b32_e32 v173, 2, v173
	global_load_dword v173, v173, s[4:5]
	v_or_b32_e32 v174, s8, v55
	v_lshlrev_b32_e32 v174, 2, v174
	global_load_dword v174, v174, s[4:5]
	v_or_b32_e32 v175, s8, v56
	v_lshlrev_b32_e32 v175, 2, v175
	global_load_dword v175, v175, s[4:5]
	v_or_b32_e32 v176, s8, v57
	v_lshlrev_b32_e32 v176, 2, v176
	global_load_dword v176, v176, s[4:5]
	v_or_b32_e32 v177, s8, v58
	v_lshlrev_b32_e32 v177, 2, v177
	global_load_dword v177, v177, s[4:5]
	v_or_b32_e32 v178, s8, v67
	v_lshlrev_b32_e32 v178, 2, v178
	global_load_dword v178, v178, s[4:5]
	v_or_b32_e32 v179, s8, v68
	v_lshlrev_b32_e32 v179, 2, v179
	global_load_dword v179, v179, s[4:5]
	v_or_b32_e32 v180, s8, v69
	v_lshlrev_b32_e32 v180, 2, v180
	global_load_dword v180, v180, s[4:5]
	v_or_b32_e32 v181, s8, v70
	v_lshlrev_b32_e32 v181, 2, v181
	global_load_dword v181, v181, s[4:5]
	s_waitcnt vmcnt(0)
	v_lshlrev_b32_e32 v23, 2, v71
	v_mov_b32_e32 v23, v150
	v_or_b32_e32 v71, s8, v32
	v_lshlrev_b32_e32 v71, 2, v71
	v_mov_b32_e32 v71, v151
	s_waitcnt vmcnt(1)
	v_mul_f32_e32 v4, v4, v23
	v_add_u32_e32 v23, v1, v24
	ds_write_b32 v23, v4
	v_or_b32_e32 v4, s8, v30
	v_lshlrev_b32_e32 v4, 2, v4
	v_mov_b32_e32 v4, v152
	v_add_u32_e32 v23, v1, v31
	s_waitcnt vmcnt(1)
	v_mul_f32_e32 v71, v76, v71
	s_waitcnt vmcnt(0)
	v_mul_f32_e32 v4, v73, v4
	ds_write2_b32 v23, v4, v71 offset1:66
	v_or_b32_e32 v4, s8, v33
	v_or_b32_e32 v71, s8, v34
	v_lshlrev_b32_e32 v4, 2, v4
	v_lshlrev_b32_e32 v71, 2, v71
	v_mov_b32_e32 v4, v153
	s_nop 0
	v_mov_b32_e32 v71, v154
	s_waitcnt vmcnt(1)
	v_mul_f32_e32 v4, v77, v4
	s_waitcnt vmcnt(0)
	v_mul_f32_e32 v71, v78, v71
	ds_write2_b32 v23, v4, v71 offset0:132 offset1:198
	v_or_b32_e32 v4, s8, v35
	v_or_b32_e32 v71, s8, v36
	v_lshlrev_b32_e32 v4, 2, v4
	v_lshlrev_b32_e32 v71, 2, v71
	v_mov_b32_e32 v4, v155
	v_add_u32_e32 v23, 0x400, v23
	v_mov_b32_e32 v71, v156
	s_waitcnt vmcnt(1)
	v_mul_f32_e32 v4, v79, v4
	s_waitcnt vmcnt(0)
	v_mul_f32_e32 v71, v80, v71
	ds_write2_b32 v23, v4, v71 offset0:8 offset1:74
	v_or_b32_e32 v4, s8, v37
	v_or_b32_e32 v23, s8, v38
	v_lshlrev_b32_e32 v4, 2, v4
	v_lshlrev_b32_e32 v23, 2, v23
	v_mov_b32_e32 v4, v157
	v_add_u32_e32 v71, 0x400, v59
	v_mov_b32_e32 v23, v158
	s_waitcnt vmcnt(1)
	v_mul_f32_e32 v4, v81, v4
	s_waitcnt vmcnt(0)
	v_mul_f32_e32 v23, v82, v23
	ds_write2_b32 v59, v4, v23 offset1:66
	v_or_b32_e32 v4, s8, v39
	v_or_b32_e32 v23, s8, v40
	v_lshlrev_b32_e32 v4, 2, v4
	v_lshlrev_b32_e32 v23, 2, v23
	v_mov_b32_e32 v4, v159
	s_nop 0
	v_mov_b32_e32 v23, v160
	s_waitcnt vmcnt(1)
	v_mul_f32_e32 v4, v83, v4
	s_waitcnt vmcnt(0)
	v_mul_f32_e32 v23, v84, v23
	ds_write2_b32 v59, v4, v23 offset0:132 offset1:198
	v_or_b32_e32 v4, s8, v41
	v_or_b32_e32 v23, s8, v42
	v_lshlrev_b32_e32 v4, 2, v4
	v_lshlrev_b32_e32 v23, 2, v23
	v_mov_b32_e32 v4, v161
	s_nop 0
	v_mov_b32_e32 v23, v162
	s_waitcnt vmcnt(1)
	v_mul_f32_e32 v4, v85, v4
	s_waitcnt vmcnt(0)
	v_mul_f32_e32 v23, v86, v23
	ds_write2_b32 v71, v4, v23 offset0:8 offset1:74
	v_or_b32_e32 v4, s8, v43
	v_or_b32_e32 v71, s8, v45
	v_lshlrev_b32_e32 v4, 2, v4
	v_lshlrev_b32_e32 v71, 2, v71
	v_mov_b32_e32 v4, v163
	v_add_u32_e32 v23, v1, v44
	v_mov_b32_e32 v71, v164
	v_add_u32_e32 v73, 0x400, v23
	s_waitcnt vmcnt(1)
	v_mul_f32_e32 v4, v87, v4
	s_waitcnt vmcnt(0)
	v_mul_f32_e32 v71, v88, v71
	ds_write2_b32 v23, v4, v71 offset1:66
	v_or_b32_e32 v4, s8, v46
	v_or_b32_e32 v71, s8, v47
	v_lshlrev_b32_e32 v4, 2, v4
	v_lshlrev_b32_e32 v71, 2, v71
	v_mov_b32_e32 v4, v165
	s_nop 0
	v_mov_b32_e32 v71, v166
	s_waitcnt vmcnt(1)
	v_mul_f32_e32 v4, v89, v4
	s_waitcnt vmcnt(0)
; __device__ __forceinline__ unsigned cvt_pk_f16(float lo, float hi) { const f32x2_t v = {lo, hi}; const f16x2_t h = __builtin_convertvector(v, f16x2_t); return __builtin_bit_cast(unsigned, h); }
; #define GAS __attribute__((address_space(1)))
; #define LAS __attribute__((address_space(3)))
; #define LDS_WAIT() asm volatile("s_waitcnt lgkmcnt(0)" ::: "memory")
; __device__ __forceinline__ unsigned pk2(float lo, float hi) { return f2bf(lo) | (f2bf(hi) << 16); }
; template <bool F16 = false>
; __device__ __forceinline__ void p0_transpose_item(const float* W, int K, int N, bf16* WT, const float* gk, LAS float* scr, int item, int lane) {
;     ...
;     for (int i = 0; i < 32; ++i) { const int kk = 2 * i + (lane >> 5); const float gsc = gk ? gk[k0 + kk] : 1.0f; scr[kk * 33 + (lane & 31)] = wv[i] * gsc; }
;     LDS_WAIT(); asm volatile("" ::: "memory");
;     const int c = lane & 7;
; #pragma unroll
;     for (int j = 0; j < 4; ++j) { const int n = (lane >> 3) + 8 * j; const LAS float* s = scr + (8 * c) * 33 + n;
;         v4u o;
;         if (F16) { o.x = pg8::cvt_pk_f16(s[0 * 33], s[1 * 33]); o.y = pg8::cvt_pk_f16(s[2 * 33], s[3 * 33]); o.z = pg8::cvt_pk_f16(s[4 * 33], s[5 * 33]); o.w = pg8::cvt_pk_f16(s[6 * 33], s[7 * 33]); }
;         else { o.x = pk2(s[0 * 33], s[1 * 33]); o.y = pk2(s[2 * 33], s[3 * 33]); o.z = pk2(s[4 * 33], s[5 * 33]); o.w = pk2(s[6 * 33], s[7 * 33]); }
;         *(GAS v4u*)(WT + (size_t)(n0 + n) * K + k0 + 8 * c) = o; }
	v_mul_f32_e32 v71, v90, v71
	ds_write2_b32 v23, v4, v71 offset0:132 offset1:198
	v_or_b32_e32 v4, s8, v48
	v_or_b32_e32 v71, s8, v49
	v_lshlrev_b32_e32 v4, 2, v4
	v_lshlrev_b32_e32 v71, 2, v71
	v_mov_b32_e32 v4, v167
	s_nop 0
	v_mov_b32_e32 v71, v168
	s_waitcnt vmcnt(1)
	v_mul_f32_e32 v4, v91, v4
	s_waitcnt vmcnt(0)
	v_mul_f32_e32 v71, v92, v71
	ds_write2_b32 v73, v4, v71 offset0:8 offset1:74
	v_or_b32_e32 v4, s8, v50
	v_or_b32_e32 v71, s8, v51
	v_lshlrev_b32_e32 v4, 2, v4
	v_lshlrev_b32_e32 v71, 2, v71
	v_mov_b32_e32 v4, v169
	s_nop 0
	v_mov_b32_e32 v71, v170
	s_waitcnt vmcnt(1)
	v_mul_f32_e32 v4, v93, v4
	s_waitcnt vmcnt(0)
	v_mul_f32_e32 v71, v94, v71
	ds_write2_b32 v73, v4, v71 offset0:140 offset1:206
	v_or_b32_e32 v4, s8, v52
	v_or_b32_e32 v71, s8, v53
	v_lshlrev_b32_e32 v4, 2, v4
	v_lshlrev_b32_e32 v71, 2, v71
	v_mov_b32_e32 v4, v171
	v_add_u32_e32 v73, 0x800, v23
	v_mov_b32_e32 v71, v172
	s_waitcnt vmcnt(1)
	v_mul_f32_e32 v4, v95, v4
	s_waitcnt vmcnt(0)
	v_mul_f32_e32 v71, v96, v71
	ds_write2_b32 v73, v4, v71 offset0:16 offset1:82
	v_or_b32_e32 v4, s8, v54
	v_or_b32_e32 v71, s8, v55
	v_lshlrev_b32_e32 v4, 2, v4
	v_lshlrev_b32_e32 v71, 2, v71
	v_mov_b32_e32 v4, v173
	s_nop 0
	v_mov_b32_e32 v71, v174
	s_waitcnt vmcnt(1)
	v_mul_f32_e32 v4, v97, v4
	s_waitcnt vmcnt(0)
	v_mul_f32_e32 v71, v98, v71
	ds_write2_b32 v73, v4, v71 offset0:148 offset1:214
	v_or_b32_e32 v4, s8, v56
	v_or_b32_e32 v71, s8, v57
	v_lshlrev_b32_e32 v4, 2, v4
	v_lshlrev_b32_e32 v71, 2, v71
	v_mov_b32_e32 v4, v175
	v_add_u32_e32 v73, 0xc00, v23
	v_mov_b32_e32 v71, v176
	s_waitcnt vmcnt(1)
	v_mul_f32_e32 v4, v99, v4
	s_waitcnt vmcnt(0)
	v_mul_f32_e32 v71, v100, v71
	ds_write2_b32 v73, v4, v71 offset0:24 offset1:90
	v_or_b32_e32 v4, s8, v58
	v_or_b32_e32 v71, s8, v67
	v_lshlrev_b32_e32 v4, 2, v4
	v_lshlrev_b32_e32 v71, 2, v71
	v_mov_b32_e32 v4, v177
	s_nop 0
	v_mov_b32_e32 v71, v178
	s_waitcnt vmcnt(1)
	v_mul_f32_e32 v4, v101, v4
	s_waitcnt vmcnt(0)
	v_mul_f32_e32 v71, v102, v71
	ds_write2_b32 v73, v4, v71 offset0:156 offset1:222
	v_or_b32_e32 v4, s8, v68
	v_or_b32_e32 v71, s8, v69
	v_lshlrev_b32_e32 v4, 2, v4
	v_lshlrev_b32_e32 v71, 2, v71
	v_mov_b32_e32 v4, v179
	v_add_u32_e32 v73, 0x1000, v23
	v_mov_b32_e32 v71, v180
	s_waitcnt vmcnt(1)
	v_mul_f32_e32 v4, v103, v4
	s_waitcnt vmcnt(0)
	v_mul_f32_e32 v71, v74, v71
	ds_write2_b32 v73, v4, v71 offset0:32 offset1:98
	v_or_b32_e32 v4, s8, v70
	v_lshlrev_b32_e32 v4, 2, v4
	v_mov_b32_e32 v4, v181
	s_waitcnt vmcnt(0)
	v_mul_f32_e32 v4, v22, v4
	ds_write_b32 v23, v4 offset:4752
	s_waitcnt lgkmcnt(0)
	ds_read2_b32 v[78:79], v26 offset0:33 offset1:41
	ds_read2_b32 v[80:81], v26 offset1:8
	ds_read2_b32 v[82:83], v26 offset0:66 offset1:74
	ds_read2_b32 v[84:85], v26 offset0:99 offset1:107
	ds_read2_b32 v[86:87], v26 offset0:132 offset1:140
	ds_read2_b32 v[88:89], v26 offset0:165 offset1:173
	ds_read2_b32 v[90:91], v26 offset0:198 offset1:206
	ds_read2_b32 v[92:93], v26 offset0:231 offset1:239
	v_or_b32_e32 v4, s2, v25
	v_lshl_add_u64 v[22:23], v[8:9], 0, s[0:1]
	v_lshlrev_b32_e32 v4, 11, v4
	v_lshl_add_u64 v[94:95], v[22:23], 0, v[4:5]
	v_or_b32_e32 v4, s2, v27
	s_waitcnt lgkmcnt(6)
	v_cvt_pk_f16_f32 v74, v80, v78
	s_waitcnt lgkmcnt(4)
	v_cvt_pk_f16_f32 v75, v82, v84
	s_waitcnt lgkmcnt(2)
	v_cvt_pk_f16_f32 v76, v86, v88
	s_waitcnt lgkmcnt(0)
	v_cvt_pk_f16_f32 v77, v90, v92
	v_lshlrev_b32_e32 v4, 11, v4
	global_store_dwordx4 v[94:95], v[74:77], off
	s_nop 1
	v_cvt_pk_f16_f32 v74, v81, v79
	v_cvt_pk_f16_f32 v75, v83, v85
	v_cvt_pk_f16_f32 v76, v87, v89
	v_cvt_pk_f16_f32 v77, v91, v93
	v_lshl_add_u64 v[78:79], v[22:23], 0, v[4:5]
	global_store_dwordx4 v[78:79], v[74:77], off
	ds_read2_b32 v[78:79], v26 offset0:49 offset1:57
	ds_read2_b32 v[80:81], v26 offset0:16 offset1:24
	ds_read2_b32 v[82:83], v26 offset0:82 offset1:90
	ds_read2_b32 v[84:85], v26 offset0:115 offset1:123
	ds_read2_b32 v[86:87], v26 offset0:148 offset1:156
	ds_read2_b32 v[88:89], v26 offset0:181 offset1:189
	ds_read2_b32 v[90:91], v26 offset0:214 offset1:222
	ds_read2_b32 v[92:93], v26 offset0:247 offset1:255
	v_or_b32_e32 v4, s2, v28
	v_lshlrev_b32_e32 v4, 11, v4
	v_lshl_add_u64 v[94:95], v[22:23], 0, v[4:5]
	v_or_b32_e32 v4, s2, v29
	s_waitcnt lgkmcnt(6)
	v_cvt_pk_f16_f32 v74, v80, v78
	s_waitcnt lgkmcnt(4)
	v_cvt_pk_f16_f32 v75, v82, v84
	s_waitcnt lgkmcnt(2)
	v_cvt_pk_f16_f32 v76, v86, v88
	s_waitcnt lgkmcnt(0)
	v_cvt_pk_f16_f32 v77, v90, v92
	v_lshlrev_b32_e32 v4, 11, v4
	global_store_dwordx4 v[94:95], v[74:77], off
	v_lshl_add_u64 v[22:23], v[22:23], 0, v[4:5]
	s_nop 0
	v_cvt_pk_f16_f32 v74, v81, v79
	v_cvt_pk_f16_f32 v75, v83, v85
	v_cvt_pk_f16_f32 v76, v87, v89
	v_cvt_pk_f16_f32 v77, v91, v93
	global_store_dwordx4 v[22:23], v[74:77], off
	s_waitcnt lgkmcnt(0)
